# combined: attention back-edge rotation + MLP-in epilogue row-scale hoist + static s_setprio 1 for the leading wave half, GEMM K-loop priority flips removed
# baseline (speedup 1.0000x reference)
; #define PG8_STAGE(bufoff, gbase, voff) do { _Pragma("unroll") for (int _i = 0; _i < 2; ++_i) \
;         __builtin_amdgcn_global_load_lds((const unsigned*)((const char*)(gbase) + (voff)[_i]), (PG8_LAS unsigned*)(lds + (bufoff) + ldsw + _i * 8192), 16, 0, 0); } while (0)
; #define PG8_LDA(dst, b, h) do { _Pragma("unroll") for (int m = 0; m < 4; ++m) { if constexpr (FP8) dst##8[m] = PG8_LD32(lds + PG8_SA(b, h) + aoff + m * 2048); else { _Pragma("unroll") for (int k = 0; k < 2; ++k) dst[m][k] = *(const PG8_LAS bf16x8*)(lds + PG8_SA(b, h) + aoff + m * 2048 + k * 1024); } } } while (0)
; #define PG8_LDB(dst, b, h) do { _Pragma("unroll") for (int n = 0; n < 2; ++n) { if constexpr (FP8) dst##8[n] = PG8_LD32(lds + PG8_SB(b, h) + boff + n * 2048); else { _Pragma("unroll") for (int k = 0; k < 2; ++k) dst[n][k] = *(const PG8_LAS bf16x8*)(lds + PG8_SB(b, h) + boff + n * 2048 + k * 1024); } } } while (0)
; #define PG8_WAIT_V(n) asm volatile("s_waitcnt vmcnt(" #n ")" ::: "memory")
; #define PG8_WAIT_L(n) asm volatile("s_waitcnt lgkmcnt(" #n ")" ::: "memory")
; #define PG8_BAR __builtin_amdgcn_s_barrier()
; #define PG8_SCHED __builtin_amdgcn_sched_barrier(0)
; template <class Epi, class Sched, bool ALIGN_EPI = false, bool SP2 = false, bool FP8 = false>
; __device__ __forceinline__ void gemm_phase(PG8_LAS unsigned char* lds, const Gemm g, const Sched& S, const Epi& E, int wave_id) {
;     ...
;             PG8_LDB(B0, 0, 0); PG8_LDB(B1, 0, 1); PG8_SCHED; PG8_LDA(At, 0, 0); PG8_STAGE(PG8_SA(1, 1), a1 + hstep, voffA);
;             PG8_WAIT_V(8); PG8_WAIT_L(0); PG8_BAR; PG8_MMA(0, 0, At, B0); PG8_MMA(0, 1, At, B1); PG8_BAR; PG8_SCHED;
;             PG8_LDA(At, 0, 1); PG8_STAGE(PG8_SB(0, 0), b2, voffB); PG8_STAGE(PG8_SB(0, 1), b2 + hstep, voffB); PG8_STAGE(PG8_SA(0, 0), a2, voffA);
;             PG8_WAIT_V(8); PG8_WAIT_L(0); PG8_BAR; PG8_MMA(1, 0, At, B0); PG8_MMA(1, 1, At, B1); PG8_BAR; PG8_SCHED;
;             PG8_LDB(B0, 1, 0); PG8_LDB(B1, 1, 1); PG8_SCHED; PG8_LDA(At, 1, 0); PG8_STAGE(PG8_SA(0, 1), a2 + hstep, voffA);
;             PG8_WAIT_V(8); PG8_WAIT_L(0); PG8_BAR; PG8_MMA(0, 0, At, B0); PG8_MMA(0, 1, At, B1); PG8_BAR; PG8_SCHED;
.LBB0_419:
	ds_read_b128 v[16:19], v187
	ds_read_b128 v[20:23], v187 offset:1024
	ds_read_b128 v[24:27], v187 offset:2048
	ds_read_b128 v[28:31], v187 offset:3072
	ds_read_b128 v[0:3], v188
	ds_read_b128 v[4:7], v188 offset:1024
	ds_read_b128 v[8:11], v188 offset:2048
	ds_read_b128 v[12:15], v188 offset:3072
	s_add_u32 s34, s30, 0xfffc0080
	s_addc_u32 s35, s31, -1
	s_cmp_eq_u32 s74, 12
	s_cselect_b32 s37, s23, s35
	s_cselect_b32 s36, s66, s34
	s_cselect_b32 s35, s21, s71
	s_cselect_b32 s34, s67, s69
	v_lshl_add_u64 v[216:217], s[30:31], 0, v[168:169]
	s_add_i32 m0, s29, 0xc000
	ds_read_b128 v[176:179], v189
	ds_read_b128 v[180:183], v189 offset:1024
	ds_read_b128 v[192:195], v189 offset:2048
	ds_read_b128 v[196:199], v189 offset:3072
	ds_read_b128 v[200:203], v189 offset:4096
	ds_read_b128 v[204:207], v189 offset:5120
	ds_read_b128 v[208:211], v189 offset:6144
	ds_read_b128 v[212:215], v189 offset:7168
	global_load_lds_dwordx4 v[216:217], off
	v_lshl_add_u64 v[216:217], s[30:31], 0, v[170:171]
	s_add_i32 m0, s29, 0xe000
	s_nop 0
	global_load_lds_dwordx4 v[216:217], off
	s_waitcnt vmcnt(8)
	s_waitcnt lgkmcnt(0)
	s_barrier
	s_waitcnt lgkmcnt(0)
	v_mfma_f32_16x16x128_f8f6f4 v[156:159], v[16:23], v[176:183], v[156:159]
	v_mfma_f32_16x16x128_f8f6f4 v[152:155], v[24:31], v[176:183], v[152:155]
	v_mfma_f32_16x16x128_f8f6f4 v[148:151], v[16:23], v[192:199], v[148:151]
	v_mfma_f32_16x16x128_f8f6f4 v[136:139], v[24:31], v[192:199], v[136:139]
	v_mfma_f32_16x16x128_f8f6f4 v[124:127], v[16:23], v[200:207], v[124:127]
	v_mfma_f32_16x16x128_f8f6f4 v[120:123], v[24:31], v[200:207], v[120:123]
	v_mfma_f32_16x16x128_f8f6f4 v[108:111], v[16:23], v[208:215], v[108:111]
	v_mfma_f32_16x16x128_f8f6f4 v[104:107], v[24:31], v[208:215], v[104:107]
	v_mfma_f32_16x16x128_f8f6f4 v[144:147], v[0:7], v[176:183], v[144:147]
	v_mfma_f32_16x16x128_f8f6f4 v[140:143], v[8:15], v[176:183], v[140:143]
	v_mfma_f32_16x16x128_f8f6f4 v[132:135], v[0:7], v[192:199], v[132:135]
	v_mfma_f32_16x16x128_f8f6f4 v[128:131], v[8:15], v[192:199], v[128:131]
	v_mfma_f32_16x16x128_f8f6f4 v[116:119], v[0:7], v[200:207], v[116:119]
	v_mfma_f32_16x16x128_f8f6f4 v[112:115], v[8:15], v[200:207], v[112:115]
	v_mfma_f32_16x16x128_f8f6f4 v[100:103], v[0:7], v[208:215], v[100:103]
	v_mfma_f32_16x16x128_f8f6f4 v[96:99], v[8:15], v[208:215], v[96:99]
	s_barrier
	s_add_i32 s75, s59, s44
	v_lshl_add_u64 v[176:177], s[34:35], 0, v[162:163]
	s_mov_b32 m0, s75
	ds_read_b128 v[192:195], v189 offset:16384
	ds_read_b128 v[196:199], v189 offset:17408
	ds_read_b128 v[200:203], v189 offset:18432
	ds_read_b128 v[204:207], v189 offset:19456
	ds_read_b128 v[208:211], v189 offset:20480
	ds_read_b128 v[212:215], v189 offset:21504
	ds_read_b128 v[216:219], v189 offset:22528
	ds_read_b128 v[220:223], v189 offset:23552
	global_load_lds_dwordx4 v[176:177], off
	s_add_i32 m0, s75, 0x2000
	s_add_u32 s78, s34, 0x40000
	v_lshl_add_u64 v[178:179], s[34:35], 0, v[166:167]
	s_addc_u32 s79, s35, 0
	s_add_i32 s75, s60, s44
	global_load_lds_dwordx4 v[178:179], off
	v_lshl_add_u64 v[180:181], s[78:79], 0, v[162:163]
	s_mov_b32 m0, s75
	v_lshl_add_u64 v[182:183], s[36:37], 0, v[164:165]
	global_load_lds_dwordx4 v[180:181], off
	v_lshl_add_u64 v[180:181], s[78:79], 0, v[166:167]
	s_add_i32 m0, s75, 0x2000
	s_nop 0
	global_load_lds_dwordx4 v[180:181], off
	v_lshl_add_u64 v[180:181], s[36:37], 0, v[160:161]
	s_mov_b32 m0, s29
	s_nop 0
	global_load_lds_dwordx4 v[180:181], off
	s_mov_b32 m0, s45
	s_nop 0
	global_load_lds_dwordx4 v[182:183], off
	s_waitcnt vmcnt(8)
	s_waitcnt lgkmcnt(0)
	s_barrier
	s_waitcnt lgkmcnt(0)
	v_mfma_f32_16x16x128_f8f6f4 v[92:95], v[16:23], v[192:199], v[92:95]
	v_mfma_f32_16x16x128_f8f6f4 v[88:91], v[24:31], v[192:199], v[88:91]
	v_mfma_f32_16x16x128_f8f6f4 v[76:79], v[16:23], v[200:207], v[76:79]
	v_mfma_f32_16x16x128_f8f6f4 v[72:75], v[24:31], v[200:207], v[72:75]
	v_mfma_f32_16x16x128_f8f6f4 v[60:63], v[16:23], v[208:215], v[60:63]
	v_mfma_f32_16x16x128_f8f6f4 v[56:59], v[24:31], v[208:215], v[56:59]
	v_mfma_f32_16x16x128_f8f6f4 v[44:47], v[16:23], v[216:223], v[44:47]
	v_mfma_f32_16x16x128_f8f6f4 v[40:43], v[24:31], v[216:223], v[40:43]
	v_mfma_f32_16x16x128_f8f6f4 v[84:87], v[0:7], v[192:199], v[84:87]
	v_mfma_f32_16x16x128_f8f6f4 v[80:83], v[8:15], v[192:199], v[80:83]
	v_mfma_f32_16x16x128_f8f6f4 v[68:71], v[0:7], v[200:207], v[68:71]
	v_mfma_f32_16x16x128_f8f6f4 v[64:67], v[8:15], v[200:207], v[64:67]
	v_mfma_f32_16x16x128_f8f6f4 v[52:55], v[0:7], v[208:215], v[52:55]
	v_mfma_f32_16x16x128_f8f6f4 v[48:51], v[8:15], v[208:215], v[48:51]
	v_mfma_f32_16x16x128_f8f6f4 v[36:39], v[0:7], v[216:223], v[36:39]
	v_mfma_f32_16x16x128_f8f6f4 v[32:35], v[8:15], v[216:223], v[32:35]
	s_barrier
	s_add_i32 s75, 0, 0x18000
	s_add_i32 s78, 0, 0x1c000
	v_add_u32_e32 v12, s75, v185
	v_add_u32_e32 v28, s78, v185
	ds_read_b128 v[0:3], v12
	ds_read_b128 v[4:7], v12 offset:1024
	ds_read_b128 v[8:11], v12 offset:2048
	ds_read_b128 v[12:15], v12 offset:3072
	ds_read_b128 v[16:19], v28
	ds_read_b128 v[20:23], v28 offset:1024
	ds_read_b128 v[24:27], v28 offset:2048
	ds_read_b128 v[28:31], v28 offset:3072
	s_add_u32 s36, s36, 0x40000
	s_addc_u32 s37, s37, 0
	s_mov_b32 m0, s52
	v_lshl_add_u64 v[224:225], s[36:37], 0, v[160:161]
	ds_read_b128 v[192:195], v189 offset:32768
	ds_read_b128 v[196:199], v189 offset:33792
	ds_read_b128 v[200:203], v189 offset:34816
	ds_read_b128 v[204:207], v189 offset:35840
	ds_read_b128 v[208:211], v189 offset:36864
	ds_read_b128 v[212:215], v189 offset:37888
	ds_read_b128 v[216:219], v189 offset:38912
	ds_read_b128 v[220:223], v189 offset:39936
	global_load_lds_dwordx4 v[224:225], off
	v_lshl_add_u64 v[224:225], s[36:37], 0, v[164:165]
	s_mov_b32 m0, s53
	s_nop 0
	global_load_lds_dwordx4 v[224:225], off
	s_waitcnt vmcnt(8)
	s_waitcnt lgkmcnt(0)
	s_barrier
; #define PG8_STAGE(bufoff, gbase, voff) do { _Pragma("unroll") for (int _i = 0; _i < 2; ++_i) \
;         __builtin_amdgcn_global_load_lds((const unsigned*)((const char*)(gbase) + (voff)[_i]), (PG8_LAS unsigned*)(lds + (bufoff) + ldsw + _i * 8192), 16, 0, 0); } while (0)
; #define PG8_LDA(dst, b, h) do { _Pragma("unroll") for (int m = 0; m < 4; ++m) { if constexpr (FP8) dst##8[m] = PG8_LD32(lds + PG8_SA(b, h) + aoff + m * 2048); else { _Pragma("unroll") for (int k = 0; k < 2; ++k) dst[m][k] = *(const PG8_LAS bf16x8*)(lds + PG8_SA(b, h) + aoff + m * 2048 + k * 1024); } } } while (0)
; #define PG8_WAIT_V(n) asm volatile("s_waitcnt vmcnt(" #n ")" ::: "memory")
; #define PG8_WAIT_L(n) asm volatile("s_waitcnt lgkmcnt(" #n ")" ::: "memory")
; #define PG8_BAR __builtin_amdgcn_s_barrier()
; #define PG8_SCHED __builtin_amdgcn_sched_barrier(0)
; template <class Epi, class Sched, bool ALIGN_EPI = false, bool SP2 = false, bool FP8 = false>
; __device__ __forceinline__ void gemm_phase(PG8_LAS unsigned char* lds, const Gemm g, const Sched& S, const Epi& E, int wave_id) {
;     ...
;             PG8_WAIT_V(8); PG8_WAIT_L(0); PG8_BAR; PG8_MMA(0, 0, At, B0); PG8_MMA(0, 1, At, B1); PG8_BAR; PG8_SCHED;
;             PG8_LDA(At, 1, 1); PG8_STAGE(PG8_SB(1, 0), b3, voffB); PG8_STAGE(PG8_SB(1, 1), b3 + hstep, voffB); PG8_STAGE(PG8_SA(1, 0), a3, voffA);
;             PG8_WAIT_V(8); PG8_WAIT_L(0); PG8_BAR; PG8_MMA(1, 0, At, B0); PG8_MMA(1, 1, At, B1); PG8_BAR; PG8_SCHED;
;     __device__ __forceinline__ void operator()(const f32x4 (&acc)[2][2][4][2], const Unit& u, int wr, int wc, int fr, int fq) const {
;         const int row0 = u.pm * BM + wr * 64 + fr, col0 = u.pn * BM + wc * 32 + 8 * fq;
;         float rs[2][4];
; #pragma unroll
;         for (int ai = 0; ai < 2; ++ai)
; #pragma unroll
;             for (int m = 0; m < 4; ++m) rs[ai][m] = __hip_atomic_load(ss + row0 + ai * HALF + m * 16, __ATOMIC_RELAXED, __HIP_MEMORY_SCOPE_AGENT);
;         asm volatile("" ::: "memory");
	s_waitcnt lgkmcnt(0)
	v_mfma_f32_16x16x128_f8f6f4 v[156:159], v[0:7], v[192:199], v[156:159]
	v_mfma_f32_16x16x128_f8f6f4 v[152:155], v[8:15], v[192:199], v[152:155]
	v_mfma_f32_16x16x128_f8f6f4 v[148:151], v[0:7], v[200:207], v[148:151]
	v_mfma_f32_16x16x128_f8f6f4 v[136:139], v[8:15], v[200:207], v[136:139]
	v_mfma_f32_16x16x128_f8f6f4 v[124:127], v[0:7], v[208:215], v[124:127]
	v_mfma_f32_16x16x128_f8f6f4 v[120:123], v[8:15], v[208:215], v[120:123]
	v_mfma_f32_16x16x128_f8f6f4 v[108:111], v[0:7], v[216:223], v[108:111]
	v_mfma_f32_16x16x128_f8f6f4 v[104:107], v[8:15], v[216:223], v[104:107]
	v_mfma_f32_16x16x128_f8f6f4 v[144:147], v[16:23], v[192:199], v[144:147]
	v_mfma_f32_16x16x128_f8f6f4 v[140:143], v[24:31], v[192:199], v[140:143]
	v_mfma_f32_16x16x128_f8f6f4 v[132:135], v[16:23], v[200:207], v[132:135]
	v_mfma_f32_16x16x128_f8f6f4 v[128:131], v[24:31], v[200:207], v[128:131]
	v_mfma_f32_16x16x128_f8f6f4 v[116:119], v[16:23], v[208:215], v[116:119]
	v_mfma_f32_16x16x128_f8f6f4 v[112:115], v[24:31], v[208:215], v[112:115]
	v_mfma_f32_16x16x128_f8f6f4 v[100:103], v[16:23], v[216:223], v[100:103]
	v_mfma_f32_16x16x128_f8f6f4 v[96:99], v[24:31], v[216:223], v[96:99]
	s_barrier
	s_add_i32 s36, s75, s44
	v_lshl_add_u64 v[176:177], v[176:177], 0, s[10:11]
	s_mov_b32 m0, s36
	ds_read_b128 v[192:195], v189 offset:49152
	ds_read_b128 v[196:199], v189 offset:50176
	ds_read_b128 v[200:203], v189 offset:51200
	ds_read_b128 v[204:207], v189 offset:52224
	ds_read_b128 v[208:211], v189 offset:53248
	ds_read_b128 v[212:215], v189 offset:54272
	ds_read_b128 v[216:219], v189 offset:55296
	ds_read_b128 v[220:223], v189 offset:56320
	global_load_lds_dwordx4 v[176:177], off
	s_add_i32 m0, s36, 0x2000
	s_add_u32 s34, s34, 0x40080
	v_lshl_add_u64 v[176:177], v[178:179], 0, s[10:11]
	s_addc_u32 s35, s35, 0
	s_add_i32 s36, s78, s44
	global_load_lds_dwordx4 v[176:177], off
	v_lshl_add_u64 v[176:177], s[34:35], 0, v[162:163]
	s_mov_b32 m0, s36
	s_nop 0
	global_load_lds_dwordx4 v[176:177], off
	v_lshl_add_u64 v[176:177], s[34:35], 0, v[166:167]
	s_add_i32 m0, s36, 0x2000
	s_nop 0
	global_load_lds_dwordx4 v[176:177], off
	v_lshl_add_u64 v[176:177], v[180:181], 0, s[10:11]
	s_mov_b32 m0, s55
	s_nop 0
	global_load_lds_dwordx4 v[176:177], off
	v_lshl_add_u64 v[176:177], v[182:183], 0, s[10:11]
	s_mov_b32 m0, s56
	s_nop 0
	global_load_lds_dwordx4 v[176:177], off
	s_waitcnt vmcnt(8)
	s_waitcnt lgkmcnt(0)
	s_barrier
	s_waitcnt lgkmcnt(0)
	v_mfma_f32_16x16x128_f8f6f4 v[92:95], v[0:7], v[192:199], v[92:95]
	v_mfma_f32_16x16x128_f8f6f4 v[88:91], v[8:15], v[192:199], v[88:91]
	v_mfma_f32_16x16x128_f8f6f4 v[76:79], v[0:7], v[200:207], v[76:79]
	v_mfma_f32_16x16x128_f8f6f4 v[72:75], v[8:15], v[200:207], v[72:75]
	v_mfma_f32_16x16x128_f8f6f4 v[60:63], v[0:7], v[208:215], v[60:63]
	v_mfma_f32_16x16x128_f8f6f4 v[56:59], v[8:15], v[208:215], v[56:59]
	v_mfma_f32_16x16x128_f8f6f4 v[44:47], v[0:7], v[216:223], v[44:47]
	v_mfma_f32_16x16x128_f8f6f4 v[40:43], v[8:15], v[216:223], v[40:43]
	v_mfma_f32_16x16x128_f8f6f4 v[84:87], v[16:23], v[192:199], v[84:87]
	v_mfma_f32_16x16x128_f8f6f4 v[80:83], v[24:31], v[192:199], v[80:83]
	v_mfma_f32_16x16x128_f8f6f4 v[68:71], v[16:23], v[200:207], v[68:71]
	v_mfma_f32_16x16x128_f8f6f4 v[64:67], v[24:31], v[200:207], v[64:67]
	v_mfma_f32_16x16x128_f8f6f4 v[52:55], v[16:23], v[208:215], v[52:55]
	v_mfma_f32_16x16x128_f8f6f4 v[48:51], v[24:31], v[208:215], v[48:51]
	v_mfma_f32_16x16x128_f8f6f4 v[36:39], v[16:23], v[216:223], v[36:39]
	v_mfma_f32_16x16x128_f8f6f4 v[32:35], v[24:31], v[216:223], v[32:35]
	s_barrier
	s_add_i32 s74, s74, 2
	s_add_u32 s30, s30, 0x100
	s_addc_u32 s31, s31, 0
	s_add_u32 s69, s69, 0x100
	s_addc_u32 s71, s71, 0
	s_cmp_gt_u32 s74, 13
	s_cbranch_scc0 .LBB0_419
	v_lshl_add_u32 v4, s28, 8, v184
	v_ashrrev_i32_e32 v5, 31, v4
	s_nop 15
	s_nop 15
	v_lshl_add_u64 v[0:1], v[4:5], 2, s[8:9]
	v_lshlrev_b64 v[14:15], 13, v[4:5]
	v_lshl_add_u64 v[0:1], s[40:41], 0, v[14:15]
	v_mov_b32_e32 v8, 0
	v_mov_b32_e32 v9, 0
	v_mov_b32_e32 v10, 0
	v_mov_b32_e32 v11, 0
	v_lshl_or_b32 v2, s65, 8, v186
	v_ashrrev_i32_e32 v3, 31, v2
	v_lshl_add_u64 v[0:1], v[0:1], 0, v[2:3]
	v_or_b32_e32 v12, 16, v4
	v_ashrrev_i32_e32 v13, 31, v12
	v_lshlrev_b64 v[12:13], 13, v[12:13]
	s_mov_b32 s65, s20
	s_mov_b32 s28, s22
	s_mov_b64 s[34:35], s[26:27]
	s_mov_b64 s[30:31], s[24:25]
	s_waitcnt vmcnt(8)
;     __device__ __forceinline__ void operator()(const f32x4 (&acc)[2][2][4][2], const Unit& u, int wr, int wc, int fr, int fq) const {
;     ...
;             for (int m = 0; m < 4; ++m) rs[ai][m] = __hip_atomic_load(ss + row0 + ai * HALF + m * 16, __ATOMIC_RELAXED, __HIP_MEMORY_SCOPE_AGENT);
;         asm volatile("" ::: "memory");
; #pragma unroll
;         for (int ai = 0; ai < 2; ++ai)
; #pragma unroll
;             for (int m = 0; m < 4; ++m) {
;                 const int row = row0 + ai * HALF + m * 16;
;                 const float rstd = __builtin_amdgcn_rsqf(rs[ai][m] * (1.f / DM) + EPS) * (1.f / W1_SCALE);
; #pragma unroll
;                 for (int bj = 0; bj < 2; ++bj) {
;                     f32x4 v0 = acc[ai][bj][m][0] * rstd, v1 = acc[ai][bj][m][1] * rstd;
; #pragma unroll
;                     for (int e = 0; e < 4; ++e) { const float a = fmaxf(v0[e], 0.f), b = fmaxf(v1[e], 0.f); v0[e] = fminf(a * a, 448.f); v1[e] = fminf(b * b, 448.f); }
;                     int w0 = __builtin_amdgcn_cvt_pk_fp8_f32(v0[0], v0[1], 0, false); w0 = __builtin_amdgcn_cvt_pk_fp8_f32(v0[2], v0[3], w0, true);
;                     int w1 = __builtin_amdgcn_cvt_pk_fp8_f32(v1[0], v1[1], 0, false); w1 = __builtin_amdgcn_cvt_pk_fp8_f32(v1[2], v1[3], w1, true);
;                     *(v2u*)(O + (size_t)row * FF + col0 + bj * HALF) = (v2u){(unsigned)w0, (unsigned)w1};
	v_mov_b32_e32 v7, v226
	v_mov_b32_e32 v16, v227
	v_mov_b32_e32 v176, v228
	v_mov_b32_e32 v177, v229
	v_mov_b32_e32 v178, v230
	v_mov_b32_e32 v179, v231
	v_mov_b32_e32 v6, v232
	v_mov_b32_e32 v5, v233
	v_fmamk_f32 v7, v7, 0x3a000000, v190
	v_fmamk_f32 v14, v16, 0x3a000000, v190
	v_rsq_f32_e32 v7, v7
	v_rsq_f32_e32 v15, v14
	v_mul_f32_e32 v14, 0x3d000000, v7
	v_mul_f32_e32 v16, 0x3d000000, v15
	v_pk_mul_f32 v[20:21], v[156:157], v[14:15] op_sel_hi:[1,0]
	v_pk_mul_f32 v[24:25], v[152:153], v[14:15] op_sel_hi:[1,0]
	v_pk_mul_f32 v[18:19], v[158:159], v[14:15] op_sel_hi:[1,0]
	v_pk_mul_f32 v[22:23], v[154:155], v[14:15] op_sel_hi:[1,0]
	v_pk_mul_f32 v[26:27], v[146:147], v[14:15] op_sel_hi:[1,0]
	v_pk_mul_f32 v[28:29], v[144:145], v[14:15] op_sel_hi:[1,0]
	v_pk_mul_f32 v[30:31], v[142:143], v[14:15] op_sel_hi:[1,0]
	v_pk_mul_f32 v[14:15], v[140:141], v[14:15] op_sel_hi:[1,0]
	v_pk_mul_f32 v[140:141], v[150:151], v[16:17] op_sel_hi:[1,0]
	v_pk_mul_f32 v[142:143], v[148:149], v[16:17] op_sel_hi:[1,0]
	v_pk_mul_f32 v[138:139], v[138:139], v[16:17] op_sel_hi:[1,0]
	v_max_f32_e32 v7, 0, v20
	v_max_f32_e32 v17, 0, v24
	v_max_f32_e32 v20, 0, v21
	v_max_f32_e32 v21, 0, v25
	v_max_f32_e32 v24, 0, v28
	v_max_f32_e32 v14, 0, v14
	v_max_f32_e32 v25, 0, v29
	v_max_f32_e32 v15, 0, v15
	v_mul_f32_e32 v7, v7, v7
	v_mul_f32_e32 v17, v17, v17
	v_mul_f32_e32 v20, v20, v20
	v_mul_f32_e32 v21, v21, v21
	v_mul_f32_e32 v24, v24, v24
	v_mul_f32_e32 v14, v14, v14
	v_mul_f32_e32 v25, v25, v25
	v_mul_f32_e32 v15, v15, v15
	v_min_f32_e32 v7, 0x43e00000, v7
	v_min_f32_e32 v17, 0x43e00000, v17
	v_min_f32_e32 v20, 0x43e00000, v20
	v_min_f32_e32 v21, 0x43e00000, v21
	v_min_f32_e32 v24, 0x43e00000, v24
	v_min_f32_e32 v14, 0x43e00000, v14
	v_min_f32_e32 v25, 0x43e00000, v25
	v_min_f32_e32 v15, 0x43e00000, v15
	v_cvt_pk_fp8_f32 v8, v7, v20
	v_cvt_pk_fp8_f32 v9, v17, v21
	v_max_f32_e32 v18, 0, v18
	v_max_f32_e32 v22, 0, v22
	v_max_f32_e32 v19, 0, v19
	v_max_f32_e32 v23, 0, v23
	v_cvt_pk_fp8_f32 v10, v24, v25
	v_cvt_pk_fp8_f32 v11, v14, v15
	v_max_f32_e32 v26, 0, v26
	v_max_f32_e32 v28, 0, v30
	v_max_f32_e32 v27, 0, v27
	v_max_f32_e32 v29, 0, v31
	v_mul_f32_e32 v18, v18, v18
	v_mul_f32_e32 v22, v22, v22
	v_mul_f32_e32 v19, v19, v19
	v_mul_f32_e32 v23, v23, v23
	v_mul_f32_e32 v26, v26, v26
	v_mul_f32_e32 v28, v28, v28
	v_mul_f32_e32 v27, v27, v27
	v_mul_f32_e32 v29, v29, v29
	v_min_f32_e32 v18, 0x43e00000, v18
	v_min_f32_e32 v22, 0x43e00000, v22
	v_min_f32_e32 v19, 0x43e00000, v19
	v_min_f32_e32 v23, 0x43e00000, v23
	v_min_f32_e32 v26, 0x43e00000, v26
	v_min_f32_e32 v28, 0x43e00000, v28
	v_min_f32_e32 v27, 0x43e00000, v27
	v_min_f32_e32 v29, 0x43e00000, v29
	v_cvt_pk_fp8_f32 v8, v18, v19 op_sel:[0,0,1]
	v_cvt_pk_fp8_f32 v9, v22, v23 op_sel:[0,0,1]
	v_cvt_pk_fp8_f32 v10, v26, v27 op_sel:[0,0,1]
	v_cvt_pk_fp8_f32 v11, v28, v29 op_sel:[0,0,1]
	v_pk_mul_f32 v[14:15], v[136:137], v[16:17] op_sel_hi:[1,0]
	global_store_dwordx2 v[0:1], v[8:9], off
	global_store_dwordx2 v[0:1], v[10:11], off offset:128
	v_max_f32_e32 v8, 0, v14
	v_mul_f32_e32 v8, v8, v8
	v_min_f32_e32 v10, 0x43e00000, v8
	v_max_f32_e32 v8, 0, v143
	v_max_f32_e32 v9, 0, v15
	v_mul_f32_e32 v8, v8, v8
	v_min_f32_e32 v11, 0x43e00000, v8
	v_mul_f32_e32 v8, v9, v9
	v_min_f32_e32 v14, 0x43e00000, v8
	v_max_f32_e32 v8, 0, v140
	v_max_f32_e32 v9, 0, v138
	v_mul_f32_e32 v8, v8, v8
	v_min_f32_e32 v15, 0x43e00000, v8
	v_mul_f32_e32 v8, v9, v9
	v_max_f32_e32 v7, 0, v142
	v_min_f32_e32 v17, 0x43e00000, v8
	v_max_f32_e32 v8, 0, v141
	v_mul_f32_e32 v7, v7, v7
	v_mul_f32_e32 v8, v8, v8
	v_min_f32_e32 v7, 0x43e00000, v7
	v_min_f32_e32 v19, 0x43e00000, v8
	v_mov_b32_e32 v8, 0
	v_mov_b32_e32 v9, 0
	v_cvt_pk_fp8_f32 v8, v7, v11
	v_cvt_pk_fp8_f32 v9, v10, v14
	v_max_f32_e32 v18, 0, v139
	v_mul_f32_e32 v7, v18, v18
	v_min_f32_e32 v7, 0x43e00000, v7
	v_lshl_add_u64 v[10:11], s[40:41], 0, v[12:13]
	v_pk_mul_f32 v[12:13], v[134:135], v[16:17] op_sel_hi:[1,0]
	v_cvt_pk_fp8_f32 v8, v15, v19 op_sel:[0,0,1]
	v_cvt_pk_fp8_f32 v9, v17, v7 op_sel:[0,0,1]
	v_pk_mul_f32 v[14:15], v[132:133], v[16:17] op_sel_hi:[1,0]
	v_pk_mul_f32 v[18:19], v[130:131], v[16:17] op_sel_hi:[1,0]
	v_pk_mul_f32 v[16:17], v[128:129], v[16:17] op_sel_hi:[1,0]
	v_max_f32_e32 v12, 0, v12
	v_max_f32_e32 v7, 0, v14
	v_max_f32_e32 v14, 0, v16
	v_max_f32_e32 v16, 0, v17
	v_max_f32_e32 v17, 0, v18
	v_mul_f32_e32 v12, v12, v12
	v_mul_f32_e32 v14, v14, v14
	v_mul_f32_e32 v16, v16, v16
	v_min_f32_e32 v18, 0x43e00000, v12
	v_mul_f32_e32 v12, v17, v17
	v_min_f32_e32 v14, 0x43e00000, v14
	v_max_f32_e32 v15, 0, v15
	v_min_f32_e32 v16, 0x43e00000, v16
	v_min_f32_e32 v17, 0x43e00000, v12
	v_max_f32_e32 v12, 0, v13
	v_mov_b32_e32 v13, 0
	v_mul_f32_e32 v7, v7, v7
	v_mul_f32_e32 v15, v15, v15
	v_mul_f32_e32 v12, v12, v12
	v_cvt_pk_fp8_f32 v13, v14, v16
	v_min_f32_e32 v7, 0x43e00000, v7
	v_min_f32_e32 v15, 0x43e00000, v15
	v_max_f32_e32 v19, 0, v19
	v_min_f32_e32 v20, 0x43e00000, v12
	v_mov_b32_e32 v12, 0
	v_cvt_pk_fp8_f32 v12, v7, v15
	v_mul_f32_e32 v7, v19, v19
	v_min_f32_e32 v7, 0x43e00000, v7
	v_cvt_pk_fp8_f32 v13, v17, v7 op_sel:[0,0,1]
	v_fmamk_f32 v7, v176, 0x3a000000, v190
	v_rsq_f32_e32 v7, v7
	v_cvt_pk_fp8_f32 v12, v18, v20 op_sel:[0,0,1]
	v_lshl_add_u64 v[10:11], v[10:11], 0, v[2:3]
	global_store_dwordx2 v[10:11], v[8:9], off
	global_store_dwordx2 v[10:11], v[12:13], off offset:128
	v_mul_f32_e32 v10, 0x3d000000, v7
	v_pk_mul_f32 v[12:13], v[126:127], v[10:11] op_sel_hi:[1,0]
	v_pk_mul_f32 v[16:17], v[122:123], v[10:11] op_sel_hi:[1,0]
	v_max_f32_e32 v12, 0, v12
	v_pk_mul_f32 v[18:19], v[120:121], v[10:11] op_sel_hi:[1,0]
	v_max_f32_e32 v16, 0, v16
	v_mul_f32_e32 v12, v12, v12
;     __device__ __forceinline__ void operator()(const f32x4 (&acc)[2][2][4][2], const Unit& u, int wr, int wc, int fr, int fq) const {
;     ...
;         for (int ai = 0; ai < 2; ++ai)
; #pragma unroll
;             for (int m = 0; m < 4; ++m) {
;                 const int row = row0 + ai * HALF + m * 16;
;                 const float rstd = __builtin_amdgcn_rsqf(rs[ai][m] * (1.f / DM) + EPS) * (1.f / W1_SCALE);
; #pragma unroll
;                 for (int bj = 0; bj < 2; ++bj) {
;                     f32x4 v0 = acc[ai][bj][m][0] * rstd, v1 = acc[ai][bj][m][1] * rstd;
; #pragma unroll
;                     for (int e = 0; e < 4; ++e) { const float a = fmaxf(v0[e], 0.f), b = fmaxf(v1[e], 0.f); v0[e] = fminf(a * a, 448.f); v1[e] = fminf(b * b, 448.f); }
;                     int w0 = __builtin_amdgcn_cvt_pk_fp8_f32(v0[0], v0[1], 0, false); w0 = __builtin_amdgcn_cvt_pk_fp8_f32(v0[2], v0[3], w0, true);
;                     int w1 = __builtin_amdgcn_cvt_pk_fp8_f32(v1[0], v1[1], 0, false); w1 = __builtin_amdgcn_cvt_pk_fp8_f32(v1[2], v1[3], w1, true);
;                     *(v2u*)(O + (size_t)row * FF + col0 + bj * HALF) = (v2u){(unsigned)w0, (unsigned)w1};
	v_pk_mul_f32 v[14:15], v[124:125], v[10:11] op_sel_hi:[1,0]
	v_max_f32_e32 v11, 0, v18
	v_min_f32_e32 v18, 0x43e00000, v12
	v_mul_f32_e32 v12, v16, v16
	v_max_f32_e32 v7, 0, v14
	v_max_f32_e32 v14, 0, v15
	v_max_f32_e32 v15, 0, v19
	v_min_f32_e32 v16, 0x43e00000, v12
	v_max_f32_e32 v12, 0, v13
	v_mul_f32_e32 v7, v7, v7
	v_mul_f32_e32 v11, v11, v11
	v_mul_f32_e32 v14, v14, v14
	v_mul_f32_e32 v15, v15, v15
	v_mul_f32_e32 v12, v12, v12
	v_min_f32_e32 v7, 0x43e00000, v7
	v_min_f32_e32 v11, 0x43e00000, v11
	v_min_f32_e32 v14, 0x43e00000, v14
	v_min_f32_e32 v15, 0x43e00000, v15
	v_min_f32_e32 v19, 0x43e00000, v12
	v_mov_b32_e32 v12, 0
	v_mov_b32_e32 v13, 0
	v_cvt_pk_fp8_f32 v12, v7, v14
	v_cvt_pk_fp8_f32 v13, v11, v15
	v_max_f32_e32 v17, 0, v17
	v_mul_f32_e32 v7, v17, v17
	v_min_f32_e32 v7, 0x43e00000, v7
	v_cvt_pk_fp8_f32 v12, v18, v19 op_sel:[0,0,1]
	v_cvt_pk_fp8_f32 v13, v16, v7 op_sel:[0,0,1]
	v_pk_mul_f32 v[14:15], v[118:119], v[10:11] op_sel_hi:[1,0]
	v_pk_mul_f32 v[16:17], v[116:117], v[10:11] op_sel_hi:[1,0]
	v_pk_mul_f32 v[18:19], v[114:115], v[10:11] op_sel_hi:[1,0]
	v_pk_mul_f32 v[10:11], v[112:113], v[10:11] op_sel_hi:[1,0]
	v_max_f32_e32 v7, 0, v16
	v_max_f32_e32 v10, 0, v10
	v_mul_f32_e32 v10, v10, v10
	v_min_f32_e32 v16, 0x43e00000, v10
	v_max_f32_e32 v10, 0, v17
	v_max_f32_e32 v11, 0, v11
	v_mul_f32_e32 v10, v10, v10
	v_min_f32_e32 v17, 0x43e00000, v10
	v_mul_f32_e32 v10, v11, v11
	v_min_f32_e32 v20, 0x43e00000, v10
	v_max_f32_e32 v10, 0, v14
	v_max_f32_e32 v11, 0, v18
	v_mul_f32_e32 v10, v10, v10
	v_min_f32_e32 v14, 0x43e00000, v10
	v_mul_f32_e32 v10, v11, v11
	v_min_f32_e32 v18, 0x43e00000, v10
	v_max_f32_e32 v10, 0, v15
	v_mov_b32_e32 v11, 0
	v_mul_f32_e32 v7, v7, v7
	v_mul_f32_e32 v10, v10, v10
	v_cvt_pk_fp8_f32 v11, v16, v20
	v_min_f32_e32 v7, 0x43e00000, v7
	v_max_f32_e32 v15, 0, v19
	v_min_f32_e32 v19, 0x43e00000, v10
	v_mov_b32_e32 v10, 0
	v_cvt_pk_fp8_f32 v10, v7, v17
	v_mul_f32_e32 v7, v15, v15
	v_min_f32_e32 v7, 0x43e00000, v7
	v_or_b32_e32 v8, 32, v4
	v_cvt_pk_fp8_f32 v11, v18, v7 op_sel:[0,0,1]
	v_fmamk_f32 v7, v177, 0x3a000000, v190
	v_ashrrev_i32_e32 v9, 31, v8
	v_rsq_f32_e32 v7, v7
	v_lshlrev_b64 v[8:9], 13, v[8:9]
	v_cvt_pk_fp8_f32 v10, v14, v19 op_sel:[0,0,1]
	v_lshl_add_u64 v[8:9], s[40:41], 0, v[8:9]
	v_lshl_add_u64 v[8:9], v[8:9], 0, v[2:3]
	global_store_dwordx2 v[8:9], v[12:13], off
	global_store_dwordx2 v[8:9], v[10:11], off offset:128
	v_or_b32_e32 v8, 48, v4
	v_mul_f32_e32 v4, 0x3d000000, v7
	v_pk_mul_f32 v[10:11], v[110:111], v[4:5] op_sel_hi:[1,0]
	v_pk_mul_f32 v[14:15], v[106:107], v[4:5] op_sel_hi:[1,0]
	v_max_f32_e32 v10, 0, v10
	v_pk_mul_f32 v[12:13], v[108:109], v[4:5] op_sel_hi:[1,0]
	v_pk_mul_f32 v[16:17], v[104:105], v[4:5] op_sel_hi:[1,0]
	v_max_f32_e32 v14, 0, v14
	v_mul_f32_e32 v10, v10, v10
	v_max_f32_e32 v7, 0, v12
	v_max_f32_e32 v12, 0, v16
	v_max_f32_e32 v16, 0, v17
	v_min_f32_e32 v17, 0x43e00000, v10
	v_mul_f32_e32 v10, v14, v14
	v_max_f32_e32 v13, 0, v13
	v_min_f32_e32 v14, 0x43e00000, v10
	v_max_f32_e32 v10, 0, v11
	v_mul_f32_e32 v7, v7, v7
	v_mul_f32_e32 v12, v12, v12
	v_mul_f32_e32 v13, v13, v13
	v_mul_f32_e32 v16, v16, v16
	v_mul_f32_e32 v10, v10, v10
	v_min_f32_e32 v7, 0x43e00000, v7
	v_min_f32_e32 v12, 0x43e00000, v12
	v_min_f32_e32 v13, 0x43e00000, v13
	v_min_f32_e32 v16, 0x43e00000, v16
	v_min_f32_e32 v18, 0x43e00000, v10
	v_mov_b32_e32 v10, 0
	v_mov_b32_e32 v11, 0
	v_cvt_pk_fp8_f32 v10, v7, v13
	v_cvt_pk_fp8_f32 v11, v12, v16
	v_max_f32_e32 v15, 0, v15
	v_mul_f32_e32 v7, v15, v15
	v_min_f32_e32 v7, 0x43e00000, v7
	v_pk_mul_f32 v[12:13], v[102:103], v[4:5] op_sel_hi:[1,0]
	v_cvt_pk_fp8_f32 v10, v17, v18 op_sel:[0,0,1]
	v_cvt_pk_fp8_f32 v11, v14, v7 op_sel:[0,0,1]
	v_pk_mul_f32 v[14:15], v[100:101], v[4:5] op_sel_hi:[1,0]
	v_pk_mul_f32 v[16:17], v[98:99], v[4:5] op_sel_hi:[1,0]
	v_pk_mul_f32 v[18:19], v[96:97], v[4:5] op_sel_hi:[1,0]
	v_max_f32_e32 v12, 0, v12
	v_max_f32_e32 v4, 0, v14
	v_max_f32_e32 v7, 0, v18
	v_max_f32_e32 v14, 0, v15
	v_max_f32_e32 v15, 0, v19
	v_max_f32_e32 v16, 0, v16
	v_mul_f32_e32 v12, v12, v12
	v_mul_f32_e32 v7, v7, v7
	v_mul_f32_e32 v15, v15, v15
	v_min_f32_e32 v18, 0x43e00000, v12
	v_mul_f32_e32 v12, v16, v16
	v_min_f32_e32 v7, 0x43e00000, v7
	v_min_f32_e32 v15, 0x43e00000, v15
	v_min_f32_e32 v16, 0x43e00000, v12
	v_max_f32_e32 v12, 0, v13
	v_mov_b32_e32 v13, 0
	v_mul_f32_e32 v4, v4, v4
	v_mul_f32_e32 v14, v14, v14
	v_mul_f32_e32 v12, v12, v12
	v_cvt_pk_fp8_f32 v13, v7, v15
	v_min_f32_e32 v4, 0x43e00000, v4
	v_min_f32_e32 v14, 0x43e00000, v14
	v_max_f32_e32 v17, 0, v17
	v_min_f32_e32 v19, 0x43e00000, v12
	v_mov_b32_e32 v12, 0
	v_cvt_pk_fp8_f32 v12, v4, v14
	v_mul_f32_e32 v4, v17, v17
	v_min_f32_e32 v4, 0x43e00000, v4
	v_cvt_pk_fp8_f32 v13, v16, v4 op_sel:[0,0,1]
	v_fmamk_f32 v4, v178, 0x3a000000, v190
	v_ashrrev_i32_e32 v9, 31, v8
	v_rsq_f32_e32 v4, v4
	v_lshlrev_b64 v[8:9], 13, v[8:9]
	v_cvt_pk_fp8_f32 v12, v18, v19 op_sel:[0,0,1]
	v_lshl_add_u64 v[8:9], s[40:41], 0, v[8:9]
	v_lshl_add_u64 v[2:3], v[8:9], 0, v[2:3]
	global_store_dwordx2 v[2:3], v[10:11], off
	global_store_dwordx2 v[2:3], v[12:13], off offset:128
	v_mul_f32_e32 v2, 0x3d000000, v4
	v_pk_mul_f32 v[8:9], v[94:95], v[2:3] op_sel_hi:[1,0]
	v_pk_mul_f32 v[10:11], v[92:93], v[2:3] op_sel_hi:[1,0]
	v_pk_mul_f32 v[12:13], v[90:91], v[2:3] op_sel_hi:[1,0]
	v_max_f32_e32 v8, 0, v8
	v_max_f32_e32 v7, 0, v11
	v_max_f32_e32 v11, 0, v12
	v_mul_f32_e32 v8, v8, v8
	v_pk_mul_f32 v[14:15], v[88:89], v[2:3] op_sel_hi:[1,0]
	v_min_f32_e32 v12, 0x43e00000, v8
	v_mul_f32_e32 v8, v11, v11
	v_max_f32_e32 v3, 0, v10
	v_max_f32_e32 v4, 0, v14
	v_max_f32_e32 v10, 0, v15
	v_min_f32_e32 v11, 0x43e00000, v8
;     __device__ __forceinline__ void operator()(const f32x4 (&acc)[2][2][4][2], const Unit& u, int wr, int wc, int fr, int fq) const {
;     ...
;         for (int ai = 0; ai < 2; ++ai)
; #pragma unroll
;             for (int m = 0; m < 4; ++m) {
;                 const int row = row0 + ai * HALF + m * 16;
;                 const float rstd = __builtin_amdgcn_rsqf(rs[ai][m] * (1.f / DM) + EPS) * (1.f / W1_SCALE);
; #pragma unroll
;                 for (int bj = 0; bj < 2; ++bj) {
;                     f32x4 v0 = acc[ai][bj][m][0] * rstd, v1 = acc[ai][bj][m][1] * rstd;
; #pragma unroll
;                     for (int e = 0; e < 4; ++e) { const float a = fmaxf(v0[e], 0.f), b = fmaxf(v1[e], 0.f); v0[e] = fminf(a * a, 448.f); v1[e] = fminf(b * b, 448.f); }
;                     int w0 = __builtin_amdgcn_cvt_pk_fp8_f32(v0[0], v0[1], 0, false); w0 = __builtin_amdgcn_cvt_pk_fp8_f32(v0[2], v0[3], w0, true);
;                     int w1 = __builtin_amdgcn_cvt_pk_fp8_f32(v1[0], v1[1], 0, false); w1 = __builtin_amdgcn_cvt_pk_fp8_f32(v1[2], v1[3], w1, true);
;                     *(v2u*)(O + (size_t)row * FF + col0 + bj * HALF) = (v2u){(unsigned)w0, (unsigned)w1};
	v_max_f32_e32 v8, 0, v9
	v_mul_f32_e32 v3, v3, v3
	v_mul_f32_e32 v4, v4, v4
	v_mul_f32_e32 v7, v7, v7
	v_mul_f32_e32 v10, v10, v10
	v_mul_f32_e32 v8, v8, v8
	v_min_f32_e32 v3, 0x43e00000, v3
	v_min_f32_e32 v4, 0x43e00000, v4
	v_min_f32_e32 v7, 0x43e00000, v7
	v_min_f32_e32 v10, 0x43e00000, v10
	v_min_f32_e32 v14, 0x43e00000, v8
	v_mov_b32_e32 v8, 0
	v_mov_b32_e32 v9, 0
	v_cvt_pk_fp8_f32 v8, v3, v7
	v_cvt_pk_fp8_f32 v9, v4, v10
	v_max_f32_e32 v13, 0, v13
	v_mul_f32_e32 v3, v13, v13
	v_min_f32_e32 v3, 0x43e00000, v3
	v_cvt_pk_fp8_f32 v8, v12, v14 op_sel:[0,0,1]
	v_cvt_pk_fp8_f32 v9, v11, v3 op_sel:[0,0,1]
	v_pk_mul_f32 v[12:13], v[86:87], v[2:3] op_sel_hi:[1,0]
	v_pk_mul_f32 v[14:15], v[84:85], v[2:3] op_sel_hi:[1,0]
	v_pk_mul_f32 v[16:17], v[82:83], v[2:3] op_sel_hi:[1,0]
	v_pk_mul_f32 v[2:3], v[80:81], v[2:3] op_sel_hi:[1,0]
	v_max_f32_e32 v4, 0, v14
	v_max_f32_e32 v2, 0, v2
	v_mul_f32_e32 v2, v2, v2
	v_min_f32_e32 v7, 0x43e00000, v2
	v_max_f32_e32 v2, 0, v15
	v_max_f32_e32 v3, 0, v3
	v_mul_f32_e32 v2, v2, v2
	v_min_f32_e32 v14, 0x43e00000, v2
	v_mul_f32_e32 v2, v3, v3
	v_min_f32_e32 v15, 0x43e00000, v2
	v_max_f32_e32 v2, 0, v12
	v_max_f32_e32 v3, 0, v16
	v_mul_f32_e32 v2, v2, v2
	v_min_f32_e32 v12, 0x43e00000, v2
	v_mul_f32_e32 v2, v3, v3
	v_min_f32_e32 v16, 0x43e00000, v2
	v_max_f32_e32 v2, 0, v13
	v_mov_b32_e32 v3, 0
	v_mul_f32_e32 v4, v4, v4
	v_mul_f32_e32 v2, v2, v2
	v_cvt_pk_fp8_f32 v3, v7, v15
	v_min_f32_e32 v4, 0x43e00000, v4
	v_max_f32_e32 v13, 0, v17
	v_min_f32_e32 v17, 0x43e00000, v2
	v_mov_b32_e32 v2, 0
	v_cvt_pk_fp8_f32 v2, v4, v14
	v_mul_f32_e32 v4, v13, v13
	v_min_f32_e32 v4, 0x43e00000, v4
	v_cvt_pk_fp8_f32 v3, v16, v4 op_sel:[0,0,1]
	v_fmamk_f32 v4, v179, 0x3a000000, v190
	v_rsq_f32_e32 v4, v4
	v_cvt_pk_fp8_f32 v2, v12, v17 op_sel:[0,0,1]
	v_add_co_u32_e32 v12, vcc, s61, v0
	v_lshl_add_u64 v[10:11], v[0:1], 0, s[12:13]
	s_nop 0
	v_addc_co_u32_e32 v13, vcc, 0, v1, vcc
	global_store_dwordx2 v[12:13], v[8:9], off
	global_store_dwordx2 v[10:11], v[2:3], off offset:128
	v_mul_f32_e32 v2, 0x3d000000, v4
	v_pk_mul_f32 v[8:9], v[78:79], v[2:3] op_sel_hi:[1,0]
	v_pk_mul_f32 v[10:11], v[76:77], v[2:3] op_sel_hi:[1,0]
	v_pk_mul_f32 v[12:13], v[74:75], v[2:3] op_sel_hi:[1,0]
	v_max_f32_e32 v8, 0, v8
	v_max_f32_e32 v7, 0, v11
	v_max_f32_e32 v11, 0, v12
	v_mul_f32_e32 v8, v8, v8
	v_pk_mul_f32 v[14:15], v[72:73], v[2:3] op_sel_hi:[1,0]
	v_min_f32_e32 v12, 0x43e00000, v8
	v_mul_f32_e32 v8, v11, v11
	v_max_f32_e32 v3, 0, v10
	v_max_f32_e32 v4, 0, v14
	v_max_f32_e32 v10, 0, v15
	v_min_f32_e32 v11, 0x43e00000, v8
	v_max_f32_e32 v8, 0, v9
	v_mul_f32_e32 v3, v3, v3
	v_mul_f32_e32 v4, v4, v4
	v_mul_f32_e32 v7, v7, v7
	v_mul_f32_e32 v10, v10, v10
	v_mul_f32_e32 v8, v8, v8
	v_min_f32_e32 v3, 0x43e00000, v3
	v_min_f32_e32 v4, 0x43e00000, v4
	v_min_f32_e32 v7, 0x43e00000, v7
	v_min_f32_e32 v10, 0x43e00000, v10
	v_min_f32_e32 v14, 0x43e00000, v8
	v_mov_b32_e32 v8, 0
	v_mov_b32_e32 v9, 0
	v_cvt_pk_fp8_f32 v8, v3, v7
	v_cvt_pk_fp8_f32 v9, v4, v10
	v_max_f32_e32 v13, 0, v13
	v_mul_f32_e32 v3, v13, v13
	v_min_f32_e32 v3, 0x43e00000, v3
	v_cvt_pk_fp8_f32 v8, v12, v14 op_sel:[0,0,1]
	v_cvt_pk_fp8_f32 v9, v11, v3 op_sel:[0,0,1]
	v_pk_mul_f32 v[12:13], v[70:71], v[2:3] op_sel_hi:[1,0]
	v_pk_mul_f32 v[14:15], v[68:69], v[2:3] op_sel_hi:[1,0]
	v_pk_mul_f32 v[16:17], v[66:67], v[2:3] op_sel_hi:[1,0]
	v_pk_mul_f32 v[2:3], v[64:65], v[2:3] op_sel_hi:[1,0]
	v_max_f32_e32 v4, 0, v14
	v_max_f32_e32 v2, 0, v2
	v_mul_f32_e32 v2, v2, v2
	v_min_f32_e32 v7, 0x43e00000, v2
	v_max_f32_e32 v2, 0, v15
	v_max_f32_e32 v3, 0, v3
	v_mul_f32_e32 v2, v2, v2
	v_min_f32_e32 v14, 0x43e00000, v2
	v_mul_f32_e32 v2, v3, v3
	v_min_f32_e32 v15, 0x43e00000, v2
	v_max_f32_e32 v2, 0, v12
	v_max_f32_e32 v3, 0, v16
	v_mul_f32_e32 v2, v2, v2
	v_min_f32_e32 v12, 0x43e00000, v2
	v_mul_f32_e32 v2, v3, v3
	v_min_f32_e32 v16, 0x43e00000, v2
	v_max_f32_e32 v2, 0, v13
	v_mov_b32_e32 v3, 0
	v_mul_f32_e32 v4, v4, v4
	v_mul_f32_e32 v2, v2, v2
	v_cvt_pk_fp8_f32 v3, v7, v15
	v_min_f32_e32 v4, 0x43e00000, v4
	v_max_f32_e32 v13, 0, v17
	v_min_f32_e32 v17, 0x43e00000, v2
	v_mov_b32_e32 v2, 0
	v_cvt_pk_fp8_f32 v2, v4, v14
	v_mul_f32_e32 v4, v13, v13
	v_min_f32_e32 v4, 0x43e00000, v4
	v_cvt_pk_fp8_f32 v3, v16, v4 op_sel:[0,0,1]
	v_fmamk_f32 v4, v6, 0x3a000000, v190
	v_rsq_f32_e32 v4, v4
	v_cvt_pk_fp8_f32 v2, v12, v17 op_sel:[0,0,1]
	v_add_co_u32_e32 v6, vcc, s62, v0
	v_lshl_add_u64 v[10:11], v[0:1], 0, s[14:15]
	s_nop 0
	v_addc_co_u32_e32 v7, vcc, 0, v1, vcc
	global_store_dwordx2 v[6:7], v[8:9], off
	global_store_dwordx2 v[10:11], v[2:3], off offset:128
	v_mul_f32_e32 v2, 0x3d000000, v4
	v_pk_mul_f32 v[6:7], v[62:63], v[2:3] op_sel_hi:[1,0]
	v_pk_mul_f32 v[10:11], v[58:59], v[2:3] op_sel_hi:[1,0]
	v_max_f32_e32 v6, 0, v6
	v_pk_mul_f32 v[12:13], v[56:57], v[2:3] op_sel_hi:[1,0]
	v_max_f32_e32 v10, 0, v10
	v_mul_f32_e32 v6, v6, v6
; #define PG8_WAIT_V(n) asm volatile("s_waitcnt vmcnt(" #n ")" ::: "memory")
; #define PG8_BAR __builtin_amdgcn_s_barrier()
; template <class Epi, class Sched, bool ALIGN_EPI = false, bool SP2 = false, bool FP8 = false>
; __device__ __forceinline__ void gemm_phase(PG8_LAS unsigned char* lds, const Gemm g, const Sched& S, const Epi& E, int wave_id) {
;     ...
;         if (!has_next) break;
; #pragma unroll
;         for (int a = 0; a < 2; ++a)
; #pragma unroll
;             for (int b = 0; b < 2; ++b)
; #pragma unroll
;                 for (int m = 0; m < 4; ++m)
; #pragma unroll
;                     for (int n = 0; n < 2; ++n) acc[a][b][m][n] = (f32x4){0.f, 0.f, 0.f, 0.f};
;         cur = nxt; cA = nA; cB = nB; ++ui;
;         if constexpr (ALIGN_EPI) { if (wr == 1) PG8_BAR; }
;     }
;     PG8_WAIT_V(0);
;     if constexpr (!ALIGN_EPI) { if (wr == 0) PG8_BAR; }
;     __device__ __forceinline__ void operator()(const f32x4 (&acc)[2][2][4][2], const Unit& u, int wr, int wc, int fr, int fq) const {
;     ...
;         for (int ai = 0; ai < 2; ++ai)
; #pragma unroll
;             for (int m = 0; m < 4; ++m) {
;                 const int row = row0 + ai * HALF + m * 16;
;                 const float rstd = __builtin_amdgcn_rsqf(rs[ai][m] * (1.f / DM) + EPS) * (1.f / W1_SCALE);
; #pragma unroll
;                 for (int bj = 0; bj < 2; ++bj) {
;                     f32x4 v0 = acc[ai][bj][m][0] * rstd, v1 = acc[ai][bj][m][1] * rstd;
; #pragma unroll
;                     for (int e = 0; e < 4; ++e) { const float a = fmaxf(v0[e], 0.f), b = fmaxf(v1[e], 0.f); v0[e] = fminf(a * a, 448.f); v1[e] = fminf(b * b, 448.f); }
;                     int w0 = __builtin_amdgcn_cvt_pk_fp8_f32(v0[0], v0[1], 0, false); w0 = __builtin_amdgcn_cvt_pk_fp8_f32(v0[2], v0[3], w0, true);
;                     int w1 = __builtin_amdgcn_cvt_pk_fp8_f32(v1[0], v1[1], 0, false); w1 = __builtin_amdgcn_cvt_pk_fp8_f32(v1[2], v1[3], w1, true);
;                     *(v2u*)(O + (size_t)row * FF + col0 + bj * HALF) = (v2u){(unsigned)w0, (unsigned)w1};
	v_pk_mul_f32 v[8:9], v[60:61], v[2:3] op_sel_hi:[1,0]
	v_max_f32_e32 v4, 0, v12
	v_min_f32_e32 v12, 0x43e00000, v6
	v_mul_f32_e32 v6, v10, v10
	v_max_f32_e32 v3, 0, v8
	v_max_f32_e32 v8, 0, v9
	v_max_f32_e32 v9, 0, v13
	v_min_f32_e32 v10, 0x43e00000, v6
	v_max_f32_e32 v6, 0, v7
	v_mul_f32_e32 v3, v3, v3
	v_mul_f32_e32 v4, v4, v4
	v_mul_f32_e32 v8, v8, v8
	v_mul_f32_e32 v9, v9, v9
	v_mul_f32_e32 v6, v6, v6
	v_min_f32_e32 v3, 0x43e00000, v3
	v_min_f32_e32 v4, 0x43e00000, v4
	v_min_f32_e32 v8, 0x43e00000, v8
	v_min_f32_e32 v9, 0x43e00000, v9
	v_min_f32_e32 v13, 0x43e00000, v6
	v_mov_b32_e32 v6, 0
	v_mov_b32_e32 v7, 0
	v_cvt_pk_fp8_f32 v6, v3, v8
	v_cvt_pk_fp8_f32 v7, v4, v9
	v_max_f32_e32 v11, 0, v11
	v_mul_f32_e32 v3, v11, v11
	v_min_f32_e32 v3, 0x43e00000, v3
	v_cvt_pk_fp8_f32 v6, v12, v13 op_sel:[0,0,1]
	v_cvt_pk_fp8_f32 v7, v10, v3 op_sel:[0,0,1]
	v_pk_mul_f32 v[10:11], v[54:55], v[2:3] op_sel_hi:[1,0]
	v_pk_mul_f32 v[12:13], v[52:53], v[2:3] op_sel_hi:[1,0]
	v_pk_mul_f32 v[14:15], v[50:51], v[2:3] op_sel_hi:[1,0]
	v_pk_mul_f32 v[2:3], v[48:49], v[2:3] op_sel_hi:[1,0]
	v_max_f32_e32 v4, 0, v12
	v_max_f32_e32 v2, 0, v2
	v_mul_f32_e32 v2, v2, v2
	v_min_f32_e32 v12, 0x43e00000, v2
	v_max_f32_e32 v2, 0, v13
	v_max_f32_e32 v3, 0, v3
	v_mul_f32_e32 v2, v2, v2
	v_min_f32_e32 v13, 0x43e00000, v2
	v_mul_f32_e32 v2, v3, v3
	v_min_f32_e32 v16, 0x43e00000, v2
	v_max_f32_e32 v2, 0, v10
	v_max_f32_e32 v3, 0, v14
	v_mul_f32_e32 v2, v2, v2
	v_min_f32_e32 v10, 0x43e00000, v2
	v_mul_f32_e32 v2, v3, v3
	v_min_f32_e32 v14, 0x43e00000, v2
	v_max_f32_e32 v2, 0, v11
	v_mul_f32_e32 v4, v4, v4
	v_mul_f32_e32 v2, v2, v2
	v_mov_b32_e32 v3, 0
	v_min_f32_e32 v4, 0x43e00000, v4
	v_max_f32_e32 v11, 0, v15
	v_min_f32_e32 v15, 0x43e00000, v2
	v_mov_b32_e32 v2, 0
	v_cvt_pk_fp8_f32 v3, v12, v16
	v_cvt_pk_fp8_f32 v2, v4, v13
	v_mul_f32_e32 v4, v11, v11
	v_min_f32_e32 v4, 0x43e00000, v4
	v_cvt_pk_fp8_f32 v3, v14, v4 op_sel:[0,0,1]
	v_fmamk_f32 v4, v5, 0x3a000000, v190
	v_cvt_pk_fp8_f32 v2, v10, v15 op_sel:[0,0,1]
	v_rsq_f32_e32 v10, v4
	v_add_co_u32_e32 v4, vcc, s63, v0
	v_lshl_add_u64 v[8:9], v[0:1], 0, s[16:17]
	s_nop 0
	v_addc_co_u32_e32 v5, vcc, 0, v1, vcc
	global_store_dwordx2 v[4:5], v[6:7], off
	global_store_dwordx2 v[8:9], v[2:3], off offset:128
	v_mul_f32_e32 v2, 0x3d000000, v10
	v_pk_mul_f32 v[4:5], v[46:47], v[2:3] op_sel_hi:[1,0]
	v_pk_mul_f32 v[8:9], v[42:43], v[2:3] op_sel_hi:[1,0]
	v_max_f32_e32 v4, 0, v4
	v_pk_mul_f32 v[6:7], v[44:45], v[2:3] op_sel_hi:[1,0]
	v_pk_mul_f32 v[10:11], v[40:41], v[2:3] op_sel_hi:[1,0]
	v_max_f32_e32 v8, 0, v8
	v_mul_f32_e32 v4, v4, v4
	v_max_f32_e32 v3, 0, v6
	v_max_f32_e32 v6, 0, v10
	v_max_f32_e32 v10, 0, v11
	v_min_f32_e32 v11, 0x43e00000, v4
	v_mul_f32_e32 v4, v8, v8
	v_max_f32_e32 v7, 0, v7
	v_min_f32_e32 v8, 0x43e00000, v4
	v_max_f32_e32 v4, 0, v5
	v_mul_f32_e32 v3, v3, v3
	v_mul_f32_e32 v6, v6, v6
	v_mul_f32_e32 v7, v7, v7
	v_mul_f32_e32 v10, v10, v10
	v_mul_f32_e32 v4, v4, v4
	v_min_f32_e32 v3, 0x43e00000, v3
	v_min_f32_e32 v6, 0x43e00000, v6
	v_min_f32_e32 v7, 0x43e00000, v7
	v_min_f32_e32 v10, 0x43e00000, v10
	v_min_f32_e32 v12, 0x43e00000, v4
	v_mov_b32_e32 v4, 0
	v_mov_b32_e32 v5, 0
	v_cvt_pk_fp8_f32 v4, v3, v7
	v_cvt_pk_fp8_f32 v5, v6, v10
	v_max_f32_e32 v9, 0, v9
	v_mul_f32_e32 v3, v9, v9
	v_min_f32_e32 v3, 0x43e00000, v3
	v_cvt_pk_fp8_f32 v4, v11, v12 op_sel:[0,0,1]
	v_cvt_pk_fp8_f32 v5, v8, v3 op_sel:[0,0,1]
	v_pk_mul_f32 v[8:9], v[38:39], v[2:3] op_sel_hi:[1,0]
	v_pk_mul_f32 v[10:11], v[36:37], v[2:3] op_sel_hi:[1,0]
	v_pk_mul_f32 v[12:13], v[34:35], v[2:3] op_sel_hi:[1,0]
	v_pk_mul_f32 v[2:3], v[32:33], v[2:3] op_sel_hi:[1,0]
	v_max_f32_e32 v10, 0, v10
	v_max_f32_e32 v2, 0, v2
	v_mul_f32_e32 v2, v2, v2
	v_min_f32_e32 v14, 0x43e00000, v2
	v_max_f32_e32 v2, 0, v11
	v_max_f32_e32 v3, 0, v3
	v_mul_f32_e32 v2, v2, v2
	v_min_f32_e32 v11, 0x43e00000, v2
	v_mul_f32_e32 v2, v3, v3
	v_min_f32_e32 v15, 0x43e00000, v2
	v_max_f32_e32 v2, 0, v8
	v_max_f32_e32 v3, 0, v12
	v_mul_f32_e32 v2, v2, v2
	v_min_f32_e32 v8, 0x43e00000, v2
	v_mul_f32_e32 v2, v3, v3
	v_min_f32_e32 v12, 0x43e00000, v2
	v_max_f32_e32 v2, 0, v9
	v_mul_f32_e32 v10, v10, v10
	v_mul_f32_e32 v2, v2, v2
	v_min_f32_e32 v10, 0x43e00000, v10
	v_max_f32_e32 v9, 0, v13
	v_min_f32_e32 v13, 0x43e00000, v2
	v_mov_b32_e32 v2, 0
	v_mov_b32_e32 v3, 0
	v_cvt_pk_fp8_f32 v2, v10, v11
	v_cvt_pk_fp8_f32 v3, v14, v15
	v_mul_f32_e32 v9, v9, v9
	v_min_f32_e32 v9, 0x43e00000, v9
	v_lshl_add_u64 v[6:7], v[0:1], 0, s[18:19]
	v_cvt_pk_fp8_f32 v2, v8, v13 op_sel:[0,0,1]
	v_cvt_pk_fp8_f32 v3, v12, v9 op_sel:[0,0,1]
	v_add_co_u32_e32 v0, vcc, s64, v0
	s_nop 1
	v_addc_co_u32_e32 v1, vcc, 0, v1, vcc
	s_and_b64 vcc, exec, s[0:1]
	global_store_dwordx2 v[0:1], v[4:5], off
	global_store_dwordx2 v[6:7], v[2:3], off offset:128
	s_cbranch_vccz .LBB0_412
	s_waitcnt vmcnt(0)
	s_cmpk_gt_u32 s42, 0xff
	s_cbranch_scc1 .LBB0_423
	s_barrier
